# lean address math: scalar base + 32-bit lane offsets for staged K/V loads in all three attention loops, shared LDS-store address, paired LDS waits, static prio for waves 4-7
# speedup vs baseline: 1.0439x; 1.0224x over previous
; #define LAS __attribute__((address_space(3)))
; template <int D1, int D2, int DV>
; DI void attn_core(f32x16 (&o)[DV / 32], float& l_out, LAS unsigned char* lds, const bf16_t* q1, const bf16_t* q2,
;                   const bf16_t* k1, long ldk1, const bf16_t* k2, long ldk2, const bf16_t* vt, long ldv, int ntiles) {
;     ...
;     gload(0); sstore(0); if (ntiles > 1) { gload(1); sstore(1); } __syncthreads();
;     for (int t = 0; t < ntiles; ++t) {
;         if (t + 2 < ntiles) gload(t + 2);
;         const LAS unsigned char* kb = lds + (t & 3) * BUF; const LAS unsigned char* vb = kb + KT;
;         f32x16 p[2];
;         {
;             bf16x8 kf[2][DQK / 16];
; #pragma unroll
;             for (int hf = 0; hf < 2; ++hf)
; #pragma unroll
;                 for (int d0 = 0; d0 < DQK / 16; ++d0) kf[hf][d0] = *(const LAS bf16x8*)(kb + (32 * hf + pr) * KROW + (16 * d0 + 8 * h) * 2);
;             __builtin_amdgcn_sched_barrier(0);
;             __builtin_amdgcn_s_setprio(2);
; #pragma unroll
;             for (int d0 = 0; d0 < DQK / 16; ++d0)
; #pragma unroll
;                 for (int hf = 0; hf < 2; ++hf) p[hf] = MFMA32(kf[hf][d0], qf[d0], d0 == 0 ? negm : p[hf]);
;             __builtin_amdgcn_sched_barrier(0);
;         }
;         constexpr int NBLK = DV / 32;
;         bf16x8 vk[2][NBLK];
;     ...
;         LDVK(0, 0);
;         __builtin_amdgcn_sched_barrier(0);
;         float ta = fmaxf(fmaxf(p[0][0], p[0][1]), p[1][0]), tb = fmaxf(fmaxf(p[0][2], p[0][3]), p[1][1]);
;         ta = fmaxf(fmaxf(ta, p[1][2]), p[1][3]);
; #pragma unroll
;         for (int i = 4; i < 16; i += 4) { ta = fmaxf(fmaxf(ta, p[0][i]), p[0][i + 1]); tb = fmaxf(fmaxf(tb, p[0][i + 2]), p[0][i + 3]); ta = fmaxf(fmaxf(ta, p[1][i]), p[1][i + 1]); tb = fmaxf(fmaxf(tb, p[1][i + 2]), p[1][i + 3]); }
;         float tm = fmaxf(ta, tb);
;         if (__any(t == 0 || tm > 8.0f)) {
;             tm = fmaxf(tm, __shfl_xor(tm, 32));
;             const float dl = (t == 0 || tm > 0.f) ? tm : 0.f; mrun += dl;
;             const float alpha = __builtin_amdgcn_exp2f(-dl); lrun *= alpha;
; #pragma unroll
;             for (int i = 0; i < 16; ++i) { p[0][i] -= dl; p[1][i] -= dl; negm[i] = -mrun; }
; #pragma unroll
;             for (int b = 0; b < DV / 32; ++b)
; #pragma unroll
;                 for (int i = 0; i < 16; ++i) o[b][i] *= alpha;
;         }
;         bf16x8 pf[4]; float rs = 0.f; u32x4 wq;
.LBB0_207:
	s_or_b64 exec, exec, s[0:1]
	v_mul_u32_u24_e32 v200, 0x90, v1
	v_add_f32_e32 v1, 0, v96
	v_add_f32_e32 v1, v97, v1
	v_add_f32_e32 v1, v98, v1
	v_add_f32_e32 v1, v99, v1
	v_add_f32_e32 v1, v100, v1
	v_add_f32_e32 v1, v101, v1
	v_add_f32_e32 v1, v102, v1
	v_add_f32_e32 v1, v103, v1
	v_add_f32_e32 v1, v104, v1
	v_add_f32_e32 v1, v105, v1
	v_add_f32_e32 v1, v106, v1
	v_add_f32_e32 v1, v107, v1
	v_add_f32_e32 v1, v108, v1
	v_add_f32_e32 v1, v109, v1
	v_add_f32_e32 v1, v110, v1
	v_add_f32_e32 v1, v111, v1
	v_add_f32_e32 v1, v3, v1
	v_add_f32_e32 v1, v4, v1
	v_add_f32_e32 v1, v5, v1
	v_add_f32_e32 v1, v6, v1
	v_add_f32_e32 v1, v7, v1
	v_add_f32_e32 v1, v8, v1
	v_add_f32_e32 v1, v9, v1
	v_add_f32_e32 v1, v10, v1
	v_add_f32_e32 v1, v11, v1
	v_mad_i64_i32 v[84:85], s[0:1], v151, s7, 0
	v_mad_i64_i32 v[86:87], s[0:1], v152, s7, 0
	v_add_f32_e32 v1, v12, v1
	v_add_f32_e32 v1, v13, v1
	s_lshl_b32 s0, s4, 7
	v_add_f32_e32 v1, v14, v1
	s_and_b32 s0, s0, 0x200
	s_lshl_b32 s1, s6, 7
	v_add_f32_e32 v1, v15, v1
	s_add_i32 s0, s0, s1
	v_add_f32_e32 v1, v80, v1
	s_bfe_u32 s7, s0, 0x30007
	v_add_f32_e32 v1, v81, v1
	s_lshl_b32 s6, s7, 8
	v_add_f32_e32 v1, v82, v1
	s_add_u32 s0, s6, s28
	v_add_f32_e32 v201, v2, v1
	v_lshlrev_b64 v[2:3], 12, v[146:147]
	s_addc_u32 s1, 0, s29
	v_lshl_add_u64 v[2:3], s[0:1], 0, v[2:3]
	v_readlane_b32 s0, v243, 52
	v_lshl_add_u64 v[2:3], v[148:149], 1, v[2:3]
	v_readlane_b32 s1, v243, 53
	s_waitcnt vmcnt(1)
	ds_write_b128 v145, v[132:135] offset:64512
	s_waitcnt vmcnt(0)
	ds_write_b128 v150, v[136:139] offset:64512
	v_lshl_add_u64 v[162:163], s[0:1], 0, v[2:3]
	v_mad_u64_u32 v[2:3], s[0:1], s7, v187, v[84:85]
	v_mov_b32_e32 v145, v157
	s_add_u32 s0, s10, s42
	v_readlane_b32 s1, v243, 59
	v_lshl_add_u64 v[2:3], v[2:3], 0, v[144:145]
	s_addc_u32 s1, s1, s43
	v_lshl_add_u64 v[164:165], s[0:1], 0, v[2:3]
	v_mad_u64_u32 v[2:3], s[8:9], s7, v187, v[86:87]
	v_lshl_add_u64 v[2:3], v[2:3], 0, v[144:145]
	s_mul_i32 s44, s7, 0x840000
	s_mov_b32 s45, s24
	v_lshl_add_u64 v[166:167], s[0:1], 0, v[2:3]
	s_mov_b32 s7, 3
	v_mov_b32_e32 v1, v0
	v_mov_b32_e32 v2, v0
	v_mov_b32_e32 v3, v0
	v_mov_b32_e32 v4, v0
	v_mov_b32_e32 v5, v0
	v_mov_b32_e32 v6, v0
	v_mov_b32_e32 v7, v0
	v_mov_b32_e32 v8, v0
	v_mov_b32_e32 v9, v0
	v_mov_b32_e32 v10, v0
	v_mov_b32_e32 v11, v0
	v_mov_b32_e32 v12, v0
	v_mov_b32_e32 v13, v0
	v_mov_b32_e32 v14, v0
	v_mov_b32_e32 v15, v0
	v_readfirstlane_b32 s0, v168
	s_bitcmp1_b32 s0, 8
	s_cbranch_scc0 .Lda1_noprio
	s_setprio 1
.Lda1_noprio:
	global_load_dwordx4 v[128:131], v[162:163], off
	global_load_dwordx4 v[132:135], v[164:165], off
	global_load_dwordx4 v[136:139], v[166:167], off
	s_mov_b64 s[0:1], 0x40000
	v_lshl_add_u64 v[162:163], v[162:163], 0, s[0:1]
	s_mov_b64 s[0:1], 0x80
	v_lshl_add_u64 v[164:165], v[164:165], 0, s[0:1]
	v_lshl_add_u64 v[166:167], v[166:167], 0, s[0:1]
	v_readfirstlane_b32 s0, v162
	v_readfirstlane_b32 s1, v163
	s_nop 3
	v_subrev_u32_e32 v162, s0, v162
	v_subrev_u32_e32 v164, s0, v164
	v_subrev_u32_e32 v166, s0, v166
	s_waitcnt lgkmcnt(0)
	s_mov_b32 s7, 1
	s_movk_i32 s9, 0x6c00
	v_add3_u32 v247, s9, v200, v197
	ds_read_b128 v[140:143], v247 offset:0
	ds_read_b128 v[144:147], v247 offset:32
	ds_read_b128 v[148:151], v247 offset:64
	ds_read_b128 v[152:155], v247 offset:96
	v_add3_u32 v246, s9, v199, v197
	s_waitcnt lgkmcnt(2)
	v_mfma_f32_32x32x16_bf16 v[96:111], v[140:143], v[112:115], v[0:15]
	ds_read_b128 v[140:143], v247 offset:4608
	v_mfma_f32_32x32x16_bf16 v[96:111], v[144:147], v[116:119], v[96:111]
	ds_read_b128 v[144:147], v247 offset:4640
	s_waitcnt lgkmcnt(2)
	v_mfma_f32_32x32x16_bf16 v[96:111], v[148:151], v[120:123], v[96:111]
	ds_read_b128 v[148:151], v247 offset:4672
	v_mfma_f32_32x32x16_bf16 v[96:111], v[152:155], v[124:127], v[96:111]
	ds_read_b128 v[152:155], v247 offset:4704
	s_waitcnt lgkmcnt(2)
	v_mfma_f32_32x32x16_bf16 v[80:95], v[140:143], v[112:115], v[0:15]
	ds_read_b128 v[208:211], v246 offset:9216
	v_mfma_f32_32x32x16_bf16 v[80:95], v[144:147], v[116:119], v[80:95]
	ds_read_b128 v[212:215], v246 offset:13824
	s_waitcnt lgkmcnt(2)
	v_mfma_f32_32x32x16_bf16 v[80:95], v[148:151], v[120:123], v[80:95]
	ds_read_b128 v[216:219], v246 offset:18432
	v_mfma_f32_32x32x16_bf16 v[80:95], v[152:155], v[124:127], v[80:95]
	ds_read_b128 v[220:223], v246 offset:23040
	s_nop 15
	v_exp_f32_e32 v232, v96
	v_exp_f32_e32 v233, v97
	s_nop 0
	v_cvt_pk_bf16_f32 v224, v232, v233
	v_exp_f32_e32 v234, v98
	v_exp_f32_e32 v235, v99
	s_nop 0
	v_cvt_pk_bf16_f32 v225, v234, v235
	v_exp_f32_e32 v236, v100
	v_exp_f32_e32 v237, v101
	s_nop 0
	v_cvt_pk_bf16_f32 v226, v236, v237
	v_exp_f32_e32 v238, v102
	v_exp_f32_e32 v239, v103
	s_nop 0
	v_cvt_pk_bf16_f32 v227, v238, v239
	s_mov_b32 s26, 0x14400
	s_waitcnt vmcnt(0)
	v_add3_u32 v247, s26, v195, v196
	ds_write_b128 v247, v[128:131] offset:0
	v_add3_u32 v247, s26, v193, v156
	ds_write_b128 v247, v[132:135] offset:9216
	v_add3_u32 v247, s26, v194, v156
	ds_write_b128 v247, v[136:139] offset:9216
	s_mov_b32 s8, 0x6c00
	s_mov_b32 s9, 0xd800
	s_mov_b32 s26, 0x1b000
	s_mov_b32 s27, 0x14400
	s_nop 1
.Lda1_top:
	s_cmpk_lt_u32 s7, 129
	s_cbranch_scc0 .Lda1_nog
	global_load_dwordx4 v[128:131], v162, s[0:1]
	global_load_dwordx4 v[132:135], v164, s[0:1]
	global_load_dwordx4 v[136:139], v166, s[0:1]
	s_add_u32 s0, s0, 0x80
	s_addc_u32 s1, s1, 0
	v_add_u32_e32 v162, 0x3ff80, v162
; template <int D1, int D2, int DV>
; DI void attn_core(f32x16 (&o)[DV / 32], float& l_out, LAS unsigned char* lds, const bf16_t* q1, const bf16_t* q2,
;                   const bf16_t* k1, long ldk1, const bf16_t* k2, long ldk2, const bf16_t* vt, long ldv, int ntiles) {
;     ...
;     for (int t = 0; t < ntiles; ++t) {
;         if (t + 2 < ntiles) gload(t + 2);
;         const LAS unsigned char* kb = lds + (t & 3) * BUF; const LAS unsigned char* vb = kb + KT;
;         f32x16 p[2];
;         {
;             bf16x8 kf[2][DQK / 16];
; #pragma unroll
;             for (int hf = 0; hf < 2; ++hf)
; #pragma unroll
;                 for (int d0 = 0; d0 < DQK / 16; ++d0) kf[hf][d0] = *(const LAS bf16x8*)(kb + (32 * hf + pr) * KROW + (16 * d0 + 8 * h) * 2);
;             __builtin_amdgcn_sched_barrier(0);
;             __builtin_amdgcn_s_setprio(2);
; #pragma unroll
;             for (int d0 = 0; d0 < DQK / 16; ++d0)
; #pragma unroll
;                 for (int hf = 0; hf < 2; ++hf) p[hf] = MFMA32(kf[hf][d0], qf[d0], d0 == 0 ? negm : p[hf]);
;             __builtin_amdgcn_sched_barrier(0);
;         }
;         constexpr int NBLK = DV / 32;
;         bf16x8 vk[2][NBLK];
;     ...
;         LDVK(0, 0);
;         __builtin_amdgcn_sched_barrier(0);
;         float ta = fmaxf(fmaxf(p[0][0], p[0][1]), p[1][0]), tb = fmaxf(fmaxf(p[0][2], p[0][3]), p[1][1]);
;         ta = fmaxf(fmaxf(ta, p[1][2]), p[1][3]);
; #pragma unroll
;         for (int i = 4; i < 16; i += 4) { ta = fmaxf(fmaxf(ta, p[0][i]), p[0][i + 1]); tb = fmaxf(fmaxf(tb, p[0][i + 2]), p[0][i + 3]); ta = fmaxf(fmaxf(ta, p[1][i]), p[1][i + 1]); tb = fmaxf(fmaxf(tb, p[1][i + 2]), p[1][i + 3]); }
;         float tm = fmaxf(ta, tb);
;         if (__any(t == 0 || tm > 8.0f)) {
;             tm = fmaxf(tm, __shfl_xor(tm, 32));
;             const float dl = (t == 0 || tm > 0.f) ? tm : 0.f; mrun += dl;
;             const float alpha = __builtin_amdgcn_exp2f(-dl); lrun *= alpha;
; #pragma unroll
;             for (int i = 0; i < 16; ++i) { p[0][i] -= dl; p[1][i] -= dl; negm[i] = -mrun; }
; #pragma unroll
;             for (int b = 0; b < DV / 32; ++b)
; #pragma unroll
;                 for (int i = 0; i < 16; ++i) o[b][i] *= alpha;
;         }
;         bf16x8 pf[4]; float rs = 0.f; u32x4 wq;
;     ...
;         EXPPART(0, 0); EXPPART(0, 1); EXPPART(0, 2); EXPPART(0, 3); pf[0] = __builtin_bit_cast(bf16x8, wq);
.Lda1_nog:
	s_waitcnt lgkmcnt(2)
	v_mfma_f32_32x32x16_bf16 v[64:79], v[208:211], v[224:227], v[64:79]
	v_exp_f32_e32 v104, v104
	v_exp_f32_e32 v105, v105
	ds_read_b128 v[208:211], v246 offset:9248
	v_cvt_pk_bf16_f32 v228, v104, v105
	v_mfma_f32_32x32x16_bf16 v[48:63], v[212:215], v[224:227], v[48:63]
	v_exp_f32_e32 v106, v106
	v_exp_f32_e32 v107, v107
	ds_read_b128 v[212:215], v246 offset:13856
	v_cvt_pk_bf16_f32 v229, v106, v107
	s_waitcnt lgkmcnt(2)
	v_mfma_f32_32x32x16_bf16 v[32:47], v[216:219], v[224:227], v[32:47]
	v_exp_f32_e32 v108, v108
	v_exp_f32_e32 v109, v109
	ds_read_b128 v[216:219], v246 offset:18464
	v_cvt_pk_bf16_f32 v230, v108, v109
	v_mfma_f32_32x32x16_bf16 v[16:31], v[220:223], v[224:227], v[16:31]
	v_exp_f32_e32 v110, v110
	v_exp_f32_e32 v111, v111
	ds_read_b128 v[220:223], v246 offset:23072
	v_cvt_pk_bf16_f32 v231, v110, v111
	s_bitcmp1_b32 s7, 0
	s_cbranch_scc0 .Lda1_nobar
	s_barrier
.Lda1_nobar:
	v_add3_u32 v247, s9, v200, v197
	ds_read_b128 v[140:143], v247 offset:0
	ds_read_b128 v[144:147], v247 offset:32
	ds_read_b128 v[148:151], v247 offset:64
	ds_read_b128 v[152:155], v247 offset:96
	s_waitcnt lgkmcnt(6)
	v_mfma_f32_32x32x16_bf16 v[64:79], v[208:211], v[228:231], v[64:79]
	v_exp_f32_e32 v80, v80
	ds_read_b128 v[208:211], v246 offset:9280
	v_exp_f32_e32 v81, v81
	v_add_f32_e32 v202, v104, v105
	v_cvt_pk_bf16_f32 v224, v80, v81
	v_mfma_f32_32x32x16_bf16 v[48:63], v[212:215], v[228:231], v[48:63]
	v_exp_f32_e32 v82, v82
	ds_read_b128 v[212:215], v246 offset:13888
	v_add_f32_e32 v202, v106, v202
	v_exp_f32_e32 v83, v83
	v_add_f32_e32 v202, v107, v202
	v_cvt_pk_bf16_f32 v225, v82, v83
	s_waitcnt lgkmcnt(6)
	v_mfma_f32_32x32x16_bf16 v[32:47], v[216:219], v[228:231], v[32:47]
	v_exp_f32_e32 v84, v84
	ds_read_b128 v[216:219], v246 offset:18496
	v_add_f32_e32 v202, v108, v202
	v_exp_f32_e32 v85, v85
	v_add_f32_e32 v202, v109, v202
	v_cvt_pk_bf16_f32 v226, v84, v85
	v_mfma_f32_32x32x16_bf16 v[16:31], v[220:223], v[228:231], v[16:31]
	v_exp_f32_e32 v86, v86
	ds_read_b128 v[220:223], v246 offset:23104
	v_add_f32_e32 v202, v110, v202
	v_exp_f32_e32 v87, v87
	v_add_f32_e32 v202, v111, v202
	v_cvt_pk_bf16_f32 v227, v86, v87
	s_waitcnt lgkmcnt(6)
	v_mfma_f32_32x32x16_bf16 v[96:111], v[140:143], v[112:115], v[0:15]
	v_exp_f32_e32 v88, v88
	v_exp_f32_e32 v89, v89
	ds_read_b128 v[140:143], v247 offset:4608
	v_cvt_pk_bf16_f32 v228, v88, v89
	v_mfma_f32_32x32x16_bf16 v[96:111], v[144:147], v[116:119], v[96:111]
	v_exp_f32_e32 v90, v90
	v_exp_f32_e32 v91, v91
	ds_read_b128 v[144:147], v247 offset:4640
	v_cvt_pk_bf16_f32 v229, v90, v91
	s_waitcnt lgkmcnt(6)
	v_mfma_f32_32x32x16_bf16 v[96:111], v[148:151], v[120:123], v[96:111]
	v_exp_f32_e32 v92, v92
	v_exp_f32_e32 v93, v93
	ds_read_b128 v[148:151], v247 offset:4672
	v_cvt_pk_bf16_f32 v230, v92, v93
	v_mfma_f32_32x32x16_bf16 v[96:111], v[152:155], v[124:127], v[96:111]
	v_exp_f32_e32 v94, v94
	v_exp_f32_e32 v95, v95
	ds_read_b128 v[152:155], v247 offset:4704
	v_cvt_pk_bf16_f32 v231, v94, v95
	s_waitcnt lgkmcnt(6)
	v_mfma_f32_32x32x16_bf16 v[64:79], v[208:211], v[224:227], v[64:79]
	v_add_f32_e32 v202, v88, v202
	ds_read_b128 v[208:211], v246 offset:9312
	v_add_f32_e32 v203, v232, v233
	v_add_f32_e32 v202, v89, v202
	v_add_f32_e32 v203, v80, v203
	v_add_f32_e32 v202, v81, v202
	v_mfma_f32_32x32x16_bf16 v[48:63], v[212:215], v[224:227], v[48:63]
	v_add_f32_e32 v202, v90, v202
	ds_read_b128 v[212:215], v246 offset:13920
	v_add_f32_e32 v203, v234, v203
	v_add_f32_e32 v202, v91, v202
	v_add_f32_e32 v203, v235, v203
	v_add_f32_e32 v202, v82, v202
	v_add_f32_e32 v203, v83, v203
	s_waitcnt lgkmcnt(6)
	v_mfma_f32_32x32x16_bf16 v[32:47], v[216:219], v[224:227], v[32:47]
	v_add_f32_e32 v202, v92, v202
	ds_read_b128 v[216:219], v246 offset:18528
	v_add_f32_e32 v203, v236, v203
	v_add_f32_e32 v202, v93, v202
	v_add_f32_e32 v203, v237, v203
	v_add_f32_e32 v202, v84, v202
	v_add_f32_e32 v203, v85, v203
	v_mfma_f32_32x32x16_bf16 v[16:31], v[220:223], v[224:227], v[16:31]
	v_add_f32_e32 v202, v94, v202
	ds_read_b128 v[220:223], v246 offset:23136
	v_add_f32_e32 v203, v238, v203
	v_add_f32_e32 v202, v95, v202
	v_add_f32_e32 v203, v239, v203
	v_add_f32_e32 v202, v86, v202
	v_add_f32_e32 v203, v87, v203
	v_add_f32_e32 v202, v203, v202
	v_add_f32_e32 v201, v202, v201
	s_waitcnt lgkmcnt(6)
	v_mfma_f32_32x32x16_bf16 v[80:95], v[140:143], v[112:115], v[0:15]
	s_waitcnt vmcnt(0)
	v_exp_f32_e32 v232, v96
	v_exp_f32_e32 v233, v97
	v_add3_u32 v247, s26, v195, v196
	v_cvt_pk_bf16_f32 v224, v232, v233
	ds_write_b128 v247, v[128:131] offset:0
	v_mfma_f32_32x32x16_bf16 v[80:95], v[144:147], v[116:119], v[80:95]
	v_exp_f32_e32 v234, v98
	v_exp_f32_e32 v235, v99
	ds_write_b128 v247, v[132:135] offset:9216
	v_cvt_pk_bf16_f32 v225, v234, v235
	s_waitcnt lgkmcnt(6)
	v_mfma_f32_32x32x16_bf16 v[80:95], v[148:151], v[120:123], v[80:95]
	v_exp_f32_e32 v236, v100
	v_exp_f32_e32 v237, v101
	ds_write_b128 v247, v[136:139] offset:18432
	v_cvt_pk_bf16_f32 v226, v236, v237
	v_mfma_f32_32x32x16_bf16 v[80:95], v[152:155], v[124:127], v[80:95]
	v_exp_f32_e32 v238, v102
	v_exp_f32_e32 v239, v103
	v_add3_u32 v246, s9, v199, v197
	v_cvt_pk_bf16_f32 v227, v238, v239
	s_waitcnt lgkmcnt(5)
	v_mfma_f32_32x32x16_bf16 v[64:79], v[208:211], v[228:231], v[64:79]
	ds_read_b128 v[208:211], v246 offset:9216
	v_mfma_f32_32x32x16_bf16 v[48:63], v[212:215], v[228:231], v[48:63]
	ds_read_b128 v[212:215], v246 offset:13824
	s_waitcnt lgkmcnt(5)
	v_mfma_f32_32x32x16_bf16 v[32:47], v[216:219], v[228:231], v[32:47]
	ds_read_b128 v[216:219], v246 offset:18432
	v_mfma_f32_32x32x16_bf16 v[16:31], v[220:223], v[228:231], v[16:31]
	ds_read_b128 v[220:223], v246 offset:23040
	v_cmp_lt_f32_e32 vcc, 0x46800000, v202
	s_add_i32 s8, s8, 0x6c00
	s_cmp_eq_u32 s8, 0x21c00
	s_cselect_b32 s8, 0, s8
	s_add_i32 s9, s9, 0x6c00
	s_cmp_eq_u32 s9, 0x21c00
	s_cselect_b32 s9, 0, s9
	s_add_i32 s26, s26, 0x6c00
	s_cmp_eq_u32 s26, 0x21c00
	s_cselect_b32 s26, 0, s26
	s_add_i32 s7, s7, 1
	s_cmpk_eq_u32 s7, 132
	s_cbranch_scc1 .Lda1_exit
	s_cbranch_vccnz .Lda1_rare_l
	s_branch .Lda1_top

; template <int D1, int D2, int DV>
; DI void attn_core(f32x16 (&o)[DV / 32], float& l_out, LAS unsigned char* lds, const bf16_t* q1, const bf16_t* q2,
;                   const bf16_t* k1, long ldk1, const bf16_t* k2, long ldk2, const bf16_t* vt, long ldv, int ntiles) {
;     ...
;         __builtin_amdgcn_s_setprio(0);
;         lrun += rs;
;     ...
;         if (t + 2 < ntiles) sstore((t + 2) & 3);
;         if (t & 1) __syncthreads();
;     }
.Lda1_exit:
	s_waitcnt lgkmcnt(0)
	s_setprio 0
	s_barrier

; #define LAS __attribute__((address_space(3)))
; template <int D1, int D2, int DV>
; DI void attn_core(f32x16 (&o)[DV / 32], float& l_out, LAS unsigned char* lds, const bf16_t* q1, const bf16_t* q2,
;                   const bf16_t* k1, long ldk1, const bf16_t* k2, long ldk2, const bf16_t* vt, long ldv, int ntiles) {
;     ...
;     gload(0); sstore(0); if (ntiles > 1) { gload(1); sstore(1); } __syncthreads();
;     for (int t = 0; t < ntiles; ++t) {
;         if (t + 2 < ntiles) gload(t + 2);
;         const LAS unsigned char* kb = lds + (t & 3) * BUF; const LAS unsigned char* vb = kb + KT;
;         f32x16 p[2];
;         {
;             bf16x8 kf[2][DQK / 16];
; #pragma unroll
;             for (int hf = 0; hf < 2; ++hf)
; #pragma unroll
;                 for (int d0 = 0; d0 < DQK / 16; ++d0) kf[hf][d0] = *(const LAS bf16x8*)(kb + (32 * hf + pr) * KROW + (16 * d0 + 8 * h) * 2);
;             __builtin_amdgcn_sched_barrier(0);
;             __builtin_amdgcn_s_setprio(2);
; #pragma unroll
;             for (int d0 = 0; d0 < DQK / 16; ++d0)
; #pragma unroll
;                 for (int hf = 0; hf < 2; ++hf) p[hf] = MFMA32(kf[hf][d0], qf[d0], d0 == 0 ? negm : p[hf]);
;             __builtin_amdgcn_sched_barrier(0);
;         }
;         constexpr int NBLK = DV / 32;
;         bf16x8 vk[2][NBLK];
;     ...
;         LDVK(0, 0);
;         __builtin_amdgcn_sched_barrier(0);
;         float ta = fmaxf(fmaxf(p[0][0], p[0][1]), p[1][0]), tb = fmaxf(fmaxf(p[0][2], p[0][3]), p[1][1]);
;         ta = fmaxf(fmaxf(ta, p[1][2]), p[1][3]);
; #pragma unroll
;         for (int i = 4; i < 16; i += 4) { ta = fmaxf(fmaxf(ta, p[0][i]), p[0][i + 1]); tb = fmaxf(fmaxf(tb, p[0][i + 2]), p[0][i + 3]); ta = fmaxf(fmaxf(ta, p[1][i]), p[1][i + 1]); tb = fmaxf(fmaxf(tb, p[1][i + 2]), p[1][i + 3]); }
;         float tm = fmaxf(ta, tb);
;         if (__any(t == 0 || tm > 8.0f)) {
;             tm = fmaxf(tm, __shfl_xor(tm, 32));
;             const float dl = (t == 0 || tm > 0.f) ? tm : 0.f; mrun += dl;
;             const float alpha = __builtin_amdgcn_exp2f(-dl); lrun *= alpha;
; #pragma unroll
;             for (int i = 0; i < 16; ++i) { p[0][i] -= dl; p[1][i] -= dl; negm[i] = -mrun; }
; #pragma unroll
;             for (int b = 0; b < DV / 32; ++b)
; #pragma unroll
;                 for (int i = 0; i < 16; ++i) o[b][i] *= alpha;
;         }
;         bf16x8 pf[4]; float rs = 0.f; u32x4 wq;
.LBB0_238:
	s_or_b64 exec, exec, s[0:1]
	v_add_f32_e32 v83, 0, v111
	v_add_f32_e32 v83, v140, v83
	v_add_f32_e32 v83, v141, v83
	v_add_f32_e32 v83, v142, v83
	v_add_f32_e32 v83, v143, v83
	v_add_f32_e32 v83, v144, v83
	v_add_f32_e32 v83, v145, v83
	v_add_f32_e32 v83, v146, v83
	v_add_f32_e32 v83, v147, v83
	v_add_f32_e32 v83, v148, v83
	v_add_f32_e32 v83, v149, v83
	v_add_f32_e32 v83, v150, v83
	v_add_f32_e32 v83, v151, v83
	v_add_f32_e32 v83, v152, v83
	v_add_f32_e32 v83, v153, v83
	v_add_f32_e32 v83, v154, v83
	v_add_f32_e32 v66, v66, v83
	v_add_f32_e32 v66, v67, v66
	v_add_f32_e32 v66, v68, v66
	v_add_f32_e32 v66, v69, v66
	v_add_f32_e32 v66, v70, v66
	v_add_f32_e32 v66, v71, v66
	v_add_f32_e32 v66, v72, v66
	v_add_f32_e32 v66, v73, v66
	v_add_f32_e32 v66, v74, v66
	v_add_f32_e32 v66, v75, v66
	v_add_f32_e32 v66, v76, v66
	v_add_f32_e32 v66, v77, v66
	v_add_f32_e32 v66, v78, v66
	v_add_f32_e32 v66, v79, v66
	v_mad_i64_i32 v[84:85], s[0:1], v108, s7, 0
	v_mad_i64_i32 v[86:87], s[0:1], v109, s7, 0
	v_add_f32_e32 v66, v80, v66
	v_add_f32_e32 v66, v81, v66
	s_add_u32 s0, s6, s28
	v_add_f32_e32 v199, v82, v66
	v_lshlrev_b64 v[66:67], 12, v[104:105]
	s_addc_u32 s1, 0, s29
	v_lshl_add_u64 v[66:67], s[0:1], 0, v[66:67]
	v_readlane_b32 s0, v243, 60
	v_lshl_add_u64 v[66:67], v[106:107], 1, v[66:67]
	v_readlane_b32 s1, v243, 61
	s_waitcnt vmcnt(1)
	ds_write_b128 v65, v[132:135] offset:64512
	s_waitcnt vmcnt(0)
	ds_write_b128 v103, v[136:139] offset:64512
	v_lshl_add_u64 v[160:161], s[0:1], 0, v[66:67]
	v_lshl_add_u64 v[66:67], s[44:45], 0, v[84:85]
	v_mov_b32_e32 v103, v157
	s_add_u32 s0, s10, s42
	v_readlane_b32 s1, v243, 59
	v_lshl_add_u64 v[66:67], v[66:67], 0, v[102:103]
	s_addc_u32 s1, s1, s43
	v_lshl_add_u64 v[162:163], s[0:1], 0, v[66:67]
	v_lshl_add_u64 v[66:67], s[44:45], 0, v[86:87]
	v_lshl_add_u64 v[66:67], v[66:67], 0, v[102:103]
	v_mul_u32_u24_e32 v198, 0x90, v110
	v_lshl_add_u64 v[164:165], s[0:1], 0, v[66:67]
	s_mov_b32 s6, 3
	v_mov_b32_e32 v65, v64
	v_mov_b32_e32 v66, v64
	v_mov_b32_e32 v67, v64
	v_mov_b32_e32 v68, v64
	v_mov_b32_e32 v69, v64
	v_mov_b32_e32 v70, v64
	v_mov_b32_e32 v71, v64
	v_mov_b32_e32 v72, v64
	v_mov_b32_e32 v73, v64
	v_mov_b32_e32 v74, v64
	v_mov_b32_e32 v75, v64
	v_mov_b32_e32 v76, v64
	v_mov_b32_e32 v77, v64
	v_mov_b32_e32 v78, v64
	v_mov_b32_e32 v79, v64
	v_readfirstlane_b32 s0, v168
	s_bitcmp1_b32 s0, 8
	s_cbranch_scc0 .Lda2_noprio
	s_setprio 1
.Lda2_noprio:
	global_load_dwordx4 v[128:131], v[160:161], off
	global_load_dwordx4 v[132:135], v[162:163], off
	global_load_dwordx4 v[136:139], v[164:165], off
	s_mov_b64 s[0:1], 0x40000
	v_lshl_add_u64 v[160:161], v[160:161], 0, s[0:1]
	s_mov_b64 s[0:1], 0x80
	v_lshl_add_u64 v[162:163], v[162:163], 0, s[0:1]
	v_lshl_add_u64 v[164:165], v[164:165], 0, s[0:1]
	v_readfirstlane_b32 s0, v160
	v_readfirstlane_b32 s1, v161
	s_nop 3
	v_subrev_u32_e32 v160, s0, v160
	v_subrev_u32_e32 v162, s0, v162
	v_subrev_u32_e32 v164, s0, v164
	s_waitcnt lgkmcnt(0)
	s_mov_b32 s7, 1
	s_movk_i32 s9, 0x6c00
	v_add3_u32 v247, s9, v198, v195
	ds_read_b128 v[140:143], v247 offset:0
	ds_read_b128 v[144:147], v247 offset:32
	ds_read_b128 v[148:151], v247 offset:64
	ds_read_b128 v[152:155], v247 offset:96
	v_add3_u32 v246, s9, v197, v195
	s_waitcnt lgkmcnt(2)
	v_mfma_f32_32x32x16_bf16 v[96:111], v[140:143], v[112:115], v[64:79]
	ds_read_b128 v[140:143], v247 offset:4608
	v_mfma_f32_32x32x16_bf16 v[96:111], v[144:147], v[116:119], v[96:111]
	ds_read_b128 v[144:147], v247 offset:4640
	s_waitcnt lgkmcnt(2)
	v_mfma_f32_32x32x16_bf16 v[96:111], v[148:151], v[120:123], v[96:111]
	ds_read_b128 v[148:151], v247 offset:4672
	v_mfma_f32_32x32x16_bf16 v[96:111], v[152:155], v[124:127], v[96:111]
	ds_read_b128 v[152:155], v247 offset:4704
	s_waitcnt lgkmcnt(2)
	v_mfma_f32_32x32x16_bf16 v[80:95], v[140:143], v[112:115], v[64:79]
	ds_read_b128 v[208:211], v246 offset:9216
	v_mfma_f32_32x32x16_bf16 v[80:95], v[144:147], v[116:119], v[80:95]
	ds_read_b128 v[212:215], v246 offset:13824
	s_waitcnt lgkmcnt(2)
	v_mfma_f32_32x32x16_bf16 v[80:95], v[148:151], v[120:123], v[80:95]
	ds_read_b128 v[216:219], v246 offset:18432
	v_mfma_f32_32x32x16_bf16 v[80:95], v[152:155], v[124:127], v[80:95]
	ds_read_b128 v[220:223], v246 offset:23040
	s_nop 15
	v_exp_f32_e32 v232, v96
	v_exp_f32_e32 v233, v97
	s_nop 0
	v_cvt_pk_bf16_f32 v224, v232, v233
	v_exp_f32_e32 v234, v98
	v_exp_f32_e32 v235, v99
	s_nop 0
	v_cvt_pk_bf16_f32 v225, v234, v235
	v_exp_f32_e32 v236, v100
	v_exp_f32_e32 v237, v101
	s_nop 0
	v_cvt_pk_bf16_f32 v226, v236, v237
	v_exp_f32_e32 v238, v102
	v_exp_f32_e32 v239, v103
	s_nop 0
	v_cvt_pk_bf16_f32 v227, v238, v239
	s_mov_b32 s26, 0x14400
	s_waitcnt vmcnt(0)
	v_add3_u32 v247, s26, v193, v194
	ds_write_b128 v247, v[128:131] offset:0
	v_add3_u32 v247, s26, v167, v156
	ds_write_b128 v247, v[132:135] offset:9216
	v_add3_u32 v247, s26, v192, v156
	ds_write_b128 v247, v[136:139] offset:9216
	s_mov_b32 s8, 0x6c00
	s_mov_b32 s9, 0xd800
	s_mov_b32 s26, 0x1b000
	s_mov_b32 s27, 0x14400
	s_nop 1
.Lda2_top:
	s_cmpk_lt_u32 s7, 129
	s_cbranch_scc0 .Lda2_nog
	global_load_dwordx4 v[128:131], v160, s[0:1]
	global_load_dwordx4 v[132:135], v162, s[0:1]
	global_load_dwordx4 v[136:139], v164, s[0:1]
	s_add_u32 s0, s0, 0x80
	s_addc_u32 s1, s1, 0
	v_add_u32_e32 v160, 0x3ff80, v160
; template <int D1, int D2, int DV>
; DI void attn_core(f32x16 (&o)[DV / 32], float& l_out, LAS unsigned char* lds, const bf16_t* q1, const bf16_t* q2,
;                   const bf16_t* k1, long ldk1, const bf16_t* k2, long ldk2, const bf16_t* vt, long ldv, int ntiles) {
;     ...
;     for (int t = 0; t < ntiles; ++t) {
;         if (t + 2 < ntiles) gload(t + 2);
;         const LAS unsigned char* kb = lds + (t & 3) * BUF; const LAS unsigned char* vb = kb + KT;
;         f32x16 p[2];
;         {
;             bf16x8 kf[2][DQK / 16];
; #pragma unroll
;             for (int hf = 0; hf < 2; ++hf)
; #pragma unroll
;                 for (int d0 = 0; d0 < DQK / 16; ++d0) kf[hf][d0] = *(const LAS bf16x8*)(kb + (32 * hf + pr) * KROW + (16 * d0 + 8 * h) * 2);
;             __builtin_amdgcn_sched_barrier(0);
;             __builtin_amdgcn_s_setprio(2);
; #pragma unroll
;             for (int d0 = 0; d0 < DQK / 16; ++d0)
; #pragma unroll
;                 for (int hf = 0; hf < 2; ++hf) p[hf] = MFMA32(kf[hf][d0], qf[d0], d0 == 0 ? negm : p[hf]);
;             __builtin_amdgcn_sched_barrier(0);
;         }
;         constexpr int NBLK = DV / 32;
;         bf16x8 vk[2][NBLK];
;     ...
;         LDVK(0, 0);
;         __builtin_amdgcn_sched_barrier(0);
;         float ta = fmaxf(fmaxf(p[0][0], p[0][1]), p[1][0]), tb = fmaxf(fmaxf(p[0][2], p[0][3]), p[1][1]);
;         ta = fmaxf(fmaxf(ta, p[1][2]), p[1][3]);
; #pragma unroll
;         for (int i = 4; i < 16; i += 4) { ta = fmaxf(fmaxf(ta, p[0][i]), p[0][i + 1]); tb = fmaxf(fmaxf(tb, p[0][i + 2]), p[0][i + 3]); ta = fmaxf(fmaxf(ta, p[1][i]), p[1][i + 1]); tb = fmaxf(fmaxf(tb, p[1][i + 2]), p[1][i + 3]); }
;         float tm = fmaxf(ta, tb);
;         if (__any(t == 0 || tm > 8.0f)) {
;             tm = fmaxf(tm, __shfl_xor(tm, 32));
;             const float dl = (t == 0 || tm > 0.f) ? tm : 0.f; mrun += dl;
;             const float alpha = __builtin_amdgcn_exp2f(-dl); lrun *= alpha;
; #pragma unroll
;             for (int i = 0; i < 16; ++i) { p[0][i] -= dl; p[1][i] -= dl; negm[i] = -mrun; }
; #pragma unroll
;             for (int b = 0; b < DV / 32; ++b)
; #pragma unroll
;                 for (int i = 0; i < 16; ++i) o[b][i] *= alpha;
;         }
;         bf16x8 pf[4]; float rs = 0.f; u32x4 wq;
;     ...
;         EXPPART(0, 0); EXPPART(0, 1); EXPPART(0, 2); EXPPART(0, 3); pf[0] = __builtin_bit_cast(bf16x8, wq);
.Lda2_nog:
	s_waitcnt lgkmcnt(2)
	v_mfma_f32_32x32x16_bf16 v[0:15], v[208:211], v[224:227], v[0:15]
	v_exp_f32_e32 v104, v104
	v_exp_f32_e32 v105, v105
	ds_read_b128 v[208:211], v246 offset:9248
	v_cvt_pk_bf16_f32 v228, v104, v105
	v_mfma_f32_32x32x16_bf16 v[48:63], v[212:215], v[224:227], v[48:63]
	v_exp_f32_e32 v106, v106
	v_exp_f32_e32 v107, v107
	ds_read_b128 v[212:215], v246 offset:13856
	v_cvt_pk_bf16_f32 v229, v106, v107
	s_waitcnt lgkmcnt(2)
	v_mfma_f32_32x32x16_bf16 v[32:47], v[216:219], v[224:227], v[32:47]
	v_exp_f32_e32 v108, v108
	v_exp_f32_e32 v109, v109
	ds_read_b128 v[216:219], v246 offset:18464
	v_cvt_pk_bf16_f32 v230, v108, v109
	v_mfma_f32_32x32x16_bf16 v[16:31], v[220:223], v[224:227], v[16:31]
	v_exp_f32_e32 v110, v110
	v_exp_f32_e32 v111, v111
	ds_read_b128 v[220:223], v246 offset:23072
	v_cvt_pk_bf16_f32 v231, v110, v111
	s_bitcmp1_b32 s7, 0
	s_cbranch_scc0 .Lda2_nobar
	s_barrier
.Lda2_nobar:
	v_add3_u32 v247, s9, v198, v195
	ds_read_b128 v[140:143], v247 offset:0
	ds_read_b128 v[144:147], v247 offset:32
	ds_read_b128 v[148:151], v247 offset:64
	ds_read_b128 v[152:155], v247 offset:96
	s_waitcnt lgkmcnt(6)
	v_mfma_f32_32x32x16_bf16 v[0:15], v[208:211], v[228:231], v[0:15]
	v_exp_f32_e32 v80, v80
	ds_read_b128 v[208:211], v246 offset:9280
	v_exp_f32_e32 v81, v81
	v_add_f32_e32 v200, v104, v105
	v_cvt_pk_bf16_f32 v224, v80, v81
	v_mfma_f32_32x32x16_bf16 v[48:63], v[212:215], v[228:231], v[48:63]
	v_exp_f32_e32 v82, v82
	ds_read_b128 v[212:215], v246 offset:13888
	v_add_f32_e32 v200, v106, v200
	v_exp_f32_e32 v83, v83
	v_add_f32_e32 v200, v107, v200
	v_cvt_pk_bf16_f32 v225, v82, v83
	s_waitcnt lgkmcnt(6)
	v_mfma_f32_32x32x16_bf16 v[32:47], v[216:219], v[228:231], v[32:47]
	v_exp_f32_e32 v84, v84
	ds_read_b128 v[216:219], v246 offset:18496
	v_add_f32_e32 v200, v108, v200
	v_exp_f32_e32 v85, v85
	v_add_f32_e32 v200, v109, v200
	v_cvt_pk_bf16_f32 v226, v84, v85
	v_mfma_f32_32x32x16_bf16 v[16:31], v[220:223], v[228:231], v[16:31]
	v_exp_f32_e32 v86, v86
	ds_read_b128 v[220:223], v246 offset:23104
	v_add_f32_e32 v200, v110, v200
	v_exp_f32_e32 v87, v87
	v_add_f32_e32 v200, v111, v200
	v_cvt_pk_bf16_f32 v227, v86, v87
	s_waitcnt lgkmcnt(6)
	v_mfma_f32_32x32x16_bf16 v[96:111], v[140:143], v[112:115], v[64:79]
	v_exp_f32_e32 v88, v88
	v_exp_f32_e32 v89, v89
	ds_read_b128 v[140:143], v247 offset:4608
	v_cvt_pk_bf16_f32 v228, v88, v89
	v_mfma_f32_32x32x16_bf16 v[96:111], v[144:147], v[116:119], v[96:111]
	v_exp_f32_e32 v90, v90
	v_exp_f32_e32 v91, v91
	ds_read_b128 v[144:147], v247 offset:4640
	v_cvt_pk_bf16_f32 v229, v90, v91
	s_waitcnt lgkmcnt(6)
	v_mfma_f32_32x32x16_bf16 v[96:111], v[148:151], v[120:123], v[96:111]
	v_exp_f32_e32 v92, v92
	v_exp_f32_e32 v93, v93
	ds_read_b128 v[148:151], v247 offset:4672
	v_cvt_pk_bf16_f32 v230, v92, v93
	v_mfma_f32_32x32x16_bf16 v[96:111], v[152:155], v[124:127], v[96:111]
	v_exp_f32_e32 v94, v94
	v_exp_f32_e32 v95, v95
	ds_read_b128 v[152:155], v247 offset:4704
	v_cvt_pk_bf16_f32 v231, v94, v95
	s_waitcnt lgkmcnt(6)
	v_mfma_f32_32x32x16_bf16 v[0:15], v[208:211], v[224:227], v[0:15]
	v_add_f32_e32 v200, v88, v200
	ds_read_b128 v[208:211], v246 offset:9312
	v_add_f32_e32 v201, v232, v233
	v_add_f32_e32 v200, v89, v200
	v_add_f32_e32 v201, v80, v201
	v_add_f32_e32 v200, v81, v200
	v_mfma_f32_32x32x16_bf16 v[48:63], v[212:215], v[224:227], v[48:63]
	v_add_f32_e32 v200, v90, v200
	ds_read_b128 v[212:215], v246 offset:13920
	v_add_f32_e32 v201, v234, v201
	v_add_f32_e32 v200, v91, v200
	v_add_f32_e32 v201, v235, v201
	v_add_f32_e32 v200, v82, v200
	v_add_f32_e32 v201, v83, v201
	s_waitcnt lgkmcnt(6)
	v_mfma_f32_32x32x16_bf16 v[32:47], v[216:219], v[224:227], v[32:47]
	v_add_f32_e32 v200, v92, v200
	ds_read_b128 v[216:219], v246 offset:18528
	v_add_f32_e32 v201, v236, v201
	v_add_f32_e32 v200, v93, v200
	v_add_f32_e32 v201, v237, v201
	v_add_f32_e32 v200, v84, v200
	v_add_f32_e32 v201, v85, v201
	v_mfma_f32_32x32x16_bf16 v[16:31], v[220:223], v[224:227], v[16:31]
	v_add_f32_e32 v200, v94, v200
	ds_read_b128 v[220:223], v246 offset:23136
	v_add_f32_e32 v201, v238, v201
	v_add_f32_e32 v200, v95, v200
	v_add_f32_e32 v201, v239, v201
	v_add_f32_e32 v200, v86, v200
	v_add_f32_e32 v201, v87, v201
	v_add_f32_e32 v200, v201, v200
	v_add_f32_e32 v199, v200, v199
	s_waitcnt lgkmcnt(6)
	v_mfma_f32_32x32x16_bf16 v[80:95], v[140:143], v[112:115], v[64:79]
	s_waitcnt vmcnt(0)
	v_exp_f32_e32 v232, v96
	v_exp_f32_e32 v233, v97
	v_add3_u32 v247, s26, v193, v194
	v_cvt_pk_bf16_f32 v224, v232, v233
	ds_write_b128 v247, v[128:131] offset:0
	v_mfma_f32_32x32x16_bf16 v[80:95], v[144:147], v[116:119], v[80:95]
	v_exp_f32_e32 v234, v98
	v_exp_f32_e32 v235, v99
	ds_write_b128 v247, v[132:135] offset:9216
	v_cvt_pk_bf16_f32 v225, v234, v235
	s_waitcnt lgkmcnt(6)
	v_mfma_f32_32x32x16_bf16 v[80:95], v[148:151], v[120:123], v[80:95]
	v_exp_f32_e32 v236, v100
	v_exp_f32_e32 v237, v101
	ds_write_b128 v247, v[136:139] offset:18432
	v_cvt_pk_bf16_f32 v226, v236, v237
	v_mfma_f32_32x32x16_bf16 v[80:95], v[152:155], v[124:127], v[80:95]
	v_exp_f32_e32 v238, v102
	v_exp_f32_e32 v239, v103
	v_add3_u32 v246, s9, v197, v195
	v_cvt_pk_bf16_f32 v227, v238, v239
	s_waitcnt lgkmcnt(5)
	v_mfma_f32_32x32x16_bf16 v[0:15], v[208:211], v[228:231], v[0:15]
	ds_read_b128 v[208:211], v246 offset:9216
	v_mfma_f32_32x32x16_bf16 v[48:63], v[212:215], v[228:231], v[48:63]
	ds_read_b128 v[212:215], v246 offset:13824
	s_waitcnt lgkmcnt(5)
	v_mfma_f32_32x32x16_bf16 v[32:47], v[216:219], v[228:231], v[32:47]
	ds_read_b128 v[216:219], v246 offset:18432
	v_mfma_f32_32x32x16_bf16 v[16:31], v[220:223], v[228:231], v[16:31]
	ds_read_b128 v[220:223], v246 offset:23040
	v_cmp_lt_f32_e32 vcc, 0x46800000, v200
	s_add_i32 s8, s8, 0x6c00
	s_cmp_eq_u32 s8, 0x21c00
	s_cselect_b32 s8, 0, s8
	s_add_i32 s9, s9, 0x6c00
	s_cmp_eq_u32 s9, 0x21c00
	s_cselect_b32 s9, 0, s9
	s_add_i32 s26, s26, 0x6c00
	s_cmp_eq_u32 s26, 0x21c00
	s_cselect_b32 s26, 0, s26
	s_add_i32 s7, s7, 1
	s_cmpk_eq_u32 s7, 132
	s_cbranch_scc1 .Lda2_exit
	s_cbranch_vccnz .Lda2_rare_l
	s_branch .Lda2_top

; template <int D1, int D2, int DV>
; DI void attn_core(f32x16 (&o)[DV / 32], float& l_out, LAS unsigned char* lds, const bf16_t* q1, const bf16_t* q2,
;                   const bf16_t* k1, long ldk1, const bf16_t* k2, long ldk2, const bf16_t* vt, long ldv, int ntiles) {
;     ...
;         __builtin_amdgcn_s_setprio(0);
;         lrun += rs;
;     ...
;         if (t + 2 < ntiles) sstore((t + 2) & 3);
;         if (t & 1) __syncthreads();
;     }
.Lda2_exit:
	s_waitcnt lgkmcnt(0)
	s_setprio 0
	s_barrier
	s_branch .LBB0_189

; #define LAS __attribute__((address_space(3)))
; template <int D1, int D2, int DV>
; DI void attn_core(f32x16 (&o)[DV / 32], float& l_out, LAS unsigned char* lds, const bf16_t* q1, const bf16_t* q2,
;                   const bf16_t* k1, long ldk1, const bf16_t* k2, long ldk2, const bf16_t* vt, long ldv, int ntiles) {
;     ...
;     const int pr = (r & ~12) | ((r & 4) << 1) | ((r & 8) >> 1);
;     float mrun = 0.f, lrun = 0.f;
;     f32x16 negm;
; #pragma unroll
;     for (int i = 0; i < 16; ++i) negm[i] = 0.f;
; #pragma unroll
;     for (int b = 0; b < DV / 32; ++b)
; #pragma unroll
;         for (int i = 0; i < 16; ++i) o[b][i] = 0.f;
;     gload(0); sstore(0); if (ntiles > 1) { gload(1); sstore(1); } __syncthreads();
;     for (int t = 0; t < ntiles; ++t) {
;         if (t + 2 < ntiles) gload(t + 2);
;         const LAS unsigned char* kb = lds + (t & 3) * BUF; const LAS unsigned char* vb = kb + KT;
;         f32x16 p[2];
;         {
;             bf16x8 kf[2][DQK / 16];
; #pragma unroll
;             for (int hf = 0; hf < 2; ++hf)
; #pragma unroll
;                 for (int d0 = 0; d0 < DQK / 16; ++d0) kf[hf][d0] = *(const LAS bf16x8*)(kb + (32 * hf + pr) * KROW + (16 * d0 + 8 * h) * 2);
;             __builtin_amdgcn_sched_barrier(0);
;             __builtin_amdgcn_s_setprio(2);
; #pragma unroll
;             for (int d0 = 0; d0 < DQK / 16; ++d0)
; #pragma unroll
;                 for (int hf = 0; hf < 2; ++hf) p[hf] = MFMA32(kf[hf][d0], qf[d0], d0 == 0 ? negm : p[hf]);
;             __builtin_amdgcn_sched_barrier(0);
;         }
;         constexpr int NBLK = DV / 32;
;         bf16x8 vk[2][NBLK];
;     ...
;         LDVK(0, 0);
;         __builtin_amdgcn_sched_barrier(0);
;         float ta = fmaxf(fmaxf(p[0][0], p[0][1]), p[1][0]), tb = fmaxf(fmaxf(p[0][2], p[0][3]), p[1][1]);
;         ta = fmaxf(fmaxf(ta, p[1][2]), p[1][3]);
; #pragma unroll
;         for (int i = 4; i < 16; i += 4) { ta = fmaxf(fmaxf(ta, p[0][i]), p[0][i + 1]); tb = fmaxf(fmaxf(tb, p[0][i + 2]), p[0][i + 3]); ta = fmaxf(fmaxf(ta, p[1][i]), p[1][i + 1]); tb = fmaxf(fmaxf(tb, p[1][i + 2]), p[1][i + 3]); }
;         float tm = fmaxf(ta, tb);
;         if (__any(t == 0 || tm > 8.0f)) {
;             tm = fmaxf(tm, __shfl_xor(tm, 32));
;             const float dl = (t == 0 || tm > 0.f) ? tm : 0.f; mrun += dl;
;             const float alpha = __builtin_amdgcn_exp2f(-dl); lrun *= alpha;
; #pragma unroll
.LBB0_319:
	s_or_b64 exec, exec, s[0:1]
	v_mul_u32_u24_e32 v146, 0xd0, v1
	v_add_f32_e32 v1, 0, v64
	v_add_f32_e32 v1, v65, v1
	v_add_f32_e32 v1, v66, v1
	v_add_f32_e32 v1, v67, v1
	v_add_f32_e32 v1, v68, v1
	v_add_f32_e32 v1, v69, v1
	v_add_f32_e32 v1, v70, v1
	v_add_f32_e32 v1, v71, v1
	v_add_f32_e32 v1, v72, v1
	v_add_f32_e32 v1, v73, v1
	v_add_f32_e32 v1, v74, v1
	v_add_f32_e32 v1, v75, v1
	v_add_f32_e32 v1, v76, v1
	v_add_f32_e32 v1, v77, v1
	v_add_f32_e32 v1, v3, v1
	v_add_f32_e32 v1, v4, v1
	v_add_f32_e32 v1, v5, v1
	v_add_f32_e32 v1, v6, v1
	v_add_f32_e32 v1, v7, v1
	v_add_f32_e32 v1, v8, v1
	v_add_f32_e32 v1, v9, v1
	v_add_f32_e32 v1, v10, v1
	v_add_f32_e32 v1, v11, v1
	v_add_f32_e32 v1, v12, v1
	v_add_f32_e32 v1, v13, v1
	v_add_f32_e32 v1, v14, v1
	v_add_f32_e32 v1, v15, v1
	v_add_f32_e32 v1, v48, v1
	v_add_f32_e32 v1, v49, v1
	v_add_f32_e32 v1, v50, v1
	v_add_f32_e32 v1, v51, v1
	s_cmp_eq_u32 s5, 0
	v_add_f32_e32 v1, v52, v1
	s_cselect_b32 s5, 4, 0x84
	v_ashrrev_i32_e32 v131, 31, v130
	s_add_u32 s0, s30, s28
	v_add_f32_e32 v147, v2, v1
	v_lshlrev_b64 v[2:3], 10, v[130:131]
	s_addc_u32 s1, 0, s29
	v_lshl_add_u64 v[2:3], v[2:3], 0, s[0:1]
	v_lshl_add_u64 v[2:3], v[128:129], 1, v[2:3]
	s_mov_b64 s[8:9], 0x19f30000
	v_lshl_add_u64 v[128:129], v[2:3], 0, s[8:9]
	v_lshlrev_b64 v[2:3], 6, v[130:131]
	v_lshl_add_u64 v[2:3], v[2:3], 0, s[58:59]
	s_waitcnt vmcnt(0)
	ds_write_b128 v123, v[112:115] offset:58368
	v_lshl_add_u64 v[2:3], v[156:157], 1, v[2:3]
	s_mov_b64 s[12:13], 0x1c002f80
	v_ashrrev_i32_e32 v123, 31, v122
	v_lshl_add_u64 v[130:131], v[2:3], 0, s[12:13]
	v_lshlrev_b64 v[2:3], 10, v[122:123]
	v_lshl_add_u64 v[2:3], v[2:3], 0, s[0:1]
	v_lshl_add_u64 v[2:3], v[132:133], 1, v[2:3]
	v_lshl_add_u64 v[132:133], v[2:3], 0, s[8:9]
	v_lshlrev_b64 v[2:3], 6, v[122:123]
	v_lshl_add_u64 v[2:3], v[2:3], 0, s[58:59]
	s_add_u32 s0, s7, 0x1c210180
	v_lshl_add_u64 v[2:3], v[134:135], 1, v[2:3]
	s_addc_u32 s1, 0, 0
	v_and_b32_e32 v1, 7, v136
	v_lshl_add_u64 v[134:135], v[2:3], 0, s[12:13]
	v_lshl_add_u64 v[2:3], s[0:1], 0, v[120:121]
	v_lshlrev_b32_e32 v156, 4, v1
	v_lshl_add_u64 v[2:3], v[2:3], 0, v[156:157]
	s_mov_b32 s6, 1
	v_lshl_add_u64 v[136:137], s[18:19], 1, v[2:3]
	v_mov_b32_e32 v1, v0
	v_mov_b32_e32 v2, v0
	v_mov_b32_e32 v3, v0
	v_mov_b32_e32 v4, v0
	v_mov_b32_e32 v5, v0
	v_mov_b32_e32 v6, v0
	v_mov_b32_e32 v7, v0
	v_mov_b32_e32 v8, v0
	v_mov_b32_e32 v9, v0
	v_mov_b32_e32 v10, v0
	v_mov_b32_e32 v11, v0
	v_mov_b32_e32 v12, v0
	v_mov_b32_e32 v13, v0
	v_mov_b32_e32 v14, v0
	v_mov_b32_e32 v15, v0
	v_readfirstlane_b32 s0, v168
	s_bitcmp1_b32 s0, 8
	s_cbranch_scc0 .Lml_noprio
	s_setprio 1
.Lml_noprio:
	v_mov_b32_e32 v220, 0xf80
	v_mov_b32_e32 v221, 0xff80
	v_cndmask_b32_e64 v222, v130, v128, s[44:45]
	v_cndmask_b32_e64 v223, v134, v132, s[46:47]
	v_cndmask_b32_e64 v130, v220, v221, s[44:45]
	v_cndmask_b32_e64 v134, v220, v221, s[46:47]
	v_mov_b32_e32 v128, v222
	v_cndmask_b32_e64 v132, v222, v223, s[42:43]
	v_cndmask_b32_e64 v134, v130, v134, s[42:43]
	s_mov_b64 s[0:1], s[16:17]
	v_and_b32_e32 v220, 63, v168
	v_mul_u32_u24_e32 v220, 0xd0, v220
	v_add_u32_e32 v220, 0xc0, v220
	v_add_u32_e32 v221, v139, v140
	v_cndmask_b32_e64 v236, v220, v221, s[42:43]
	v_and_b32_e32 v220, 64, v186
	v_xor_b32_e32 v221, 32, v186
	v_add_u32_e32 v220, 64, v220
	v_cmp_lt_i32_e32 vcc, v221, v220
	s_nop 1
	v_cndmask_b32_e32 v221, v186, v221, vcc
	v_lshlrev_b32_e32 v237, 2, v221
	global_load_dwordx4 v[104:107], v128, s[0:1]
	global_load_dwordx4 v[108:111], v132, s[0:1]
	global_load_dwordx4 v[112:115], v136, s[0:1]
	s_add_u32 s0, s0, 0x80
	s_addc_u32 s1, s1, 0
	v_add_u32_e32 v128, v128, v130
	v_add_u32_e32 v132, v132, v134
	s_waitcnt lgkmcnt(0)
	s_movk_i32 s8, 0x5800
	v_add3_u32 v233, s8, v146, v141
	ds_read_b128 v[116:119], v233 offset:0
	ds_read_b128 v[120:123], v233 offset:32
	ds_read_b128 v[148:151], v233 offset:64
	ds_read_b128 v[152:155], v233 offset:96
	v_add3_u32 v232, s8, v143, v141
	s_waitcnt lgkmcnt(2)
	v_mfma_f32_32x32x16_bf16 v[64:79], v[116:119], v[80:83], v[0:15]
	ds_read_b128 v[116:119], v233 offset:128
	v_mfma_f32_32x32x16_bf16 v[64:79], v[120:123], v[84:87], v[64:79]
	ds_read_b128 v[120:123], v233 offset:160
	s_waitcnt lgkmcnt(2)
	v_mfma_f32_32x32x16_bf16 v[64:79], v[148:151], v[88:91], v[64:79]
	ds_read_b128 v[148:151], v233 offset:6656
	v_mfma_f32_32x32x16_bf16 v[64:79], v[152:155], v[92:95], v[64:79]
	ds_read_b128 v[152:155], v233 offset:6688
	s_waitcnt lgkmcnt(2)
	v_mfma_f32_32x32x16_bf16 v[64:79], v[116:119], v[96:99], v[64:79]
	ds_read_b128 v[116:119], v233 offset:6720
	v_mfma_f32_32x32x16_bf16 v[64:79], v[120:123], v[100:103], v[64:79]
	ds_read_b128 v[120:123], v233 offset:6752
	s_waitcnt lgkmcnt(2)
	v_mfma_f32_32x32x16_bf16 v[48:63], v[148:151], v[80:83], v[0:15]
	ds_read_b128 v[148:151], v233 offset:6784
	v_mfma_f32_32x32x16_bf16 v[48:63], v[152:155], v[84:87], v[48:63]
	ds_read_b128 v[152:155], v233 offset:6816
	s_waitcnt lgkmcnt(2)
	v_mfma_f32_32x32x16_bf16 v[48:63], v[116:119], v[88:91], v[48:63]
	v_mfma_f32_32x32x16_bf16 v[48:63], v[120:123], v[92:95], v[48:63]
	s_waitcnt lgkmcnt(0)
	v_mfma_f32_32x32x16_bf16 v[48:63], v[148:151], v[96:99], v[48:63]
	v_mfma_f32_32x32x16_bf16 v[48:63], v[152:155], v[100:103], v[48:63]
	ds_read_b128 v[158:161], v232 offset:13312
	ds_read_b128 v[162:165], v232 offset:17920
	ds_read_b128 v[190:193], v232 offset:13344
	ds_read_b128 v[194:197], v232 offset:17952
	s_nop 15
	v_exp_f32_e32 v216, v64
	v_exp_f32_e32 v217, v65
	v_exp_f32_e32 v218, v66
	v_exp_f32_e32 v219, v67
	v_exp_f32_e32 v220, v68
	v_exp_f32_e32 v221, v69
	v_exp_f32_e32 v222, v70
	v_exp_f32_e32 v223, v71
	v_exp_f32_e32 v224, v72
	v_exp_f32_e32 v225, v73
	v_exp_f32_e32 v226, v74
	v_exp_f32_e32 v227, v75
	v_exp_f32_e32 v228, v76
	v_exp_f32_e32 v229, v77
	v_exp_f32_e32 v230, v78
	v_exp_f32_e32 v231, v79
	s_nop 0
	v_cvt_pk_bf16_f32 v198, v216, v217
	v_cvt_pk_bf16_f32 v199, v218, v219
	v_cvt_pk_bf16_f32 v200, v220, v221
	v_cvt_pk_bf16_f32 v201, v222, v223
	v_cvt_pk_bf16_f32 v208, v224, v225
	v_cvt_pk_bf16_f32 v209, v226, v227
	v_cvt_pk_bf16_f32 v210, v228, v229
	v_cvt_pk_bf16_f32 v211, v230, v231
	s_mov_b32 s18, 0x10800
	s_waitcnt vmcnt(0)
	v_add3_u32 v233, s18, v144, v145
	ds_write_b128 v233, v[104:107] offset:0
	v_add_u32_e32 v233, s18, v236
	ds_write_b128 v233, v[108:111] offset:0
	v_add3_u32 v233, s18, v127, v126
	ds_write_b128 v233, v[112:115] offset:13312
	s_mov_b32 s7, 0x5800
	s_mov_b32 s8, 0xb000
	s_mov_b32 s18, 0x16000
	s_waitcnt lgkmcnt(0)
.Lml_top:
	s_add_i32 s19, s6, 3
	s_cmp_lt_u32 s19, s5
	s_cbranch_scc0 .Lml_nog
	global_load_dwordx4 v[104:107], v128, s[0:1]
	global_load_dwordx4 v[108:111], v132, s[0:1]
	global_load_dwordx4 v[112:115], v136, s[0:1]
	s_add_u32 s0, s0, 0x80
	s_addc_u32 s1, s1, 0
	v_add_u32_e32 v128, v128, v130
	v_add_u32_e32 v132, v132, v134

; template <int D1, int D2, int DV>
; DI void attn_core(f32x16 (&o)[DV / 32], float& l_out, LAS unsigned char* lds, const bf16_t* q1, const bf16_t* q2,
;                   const bf16_t* k1, long ldk1, const bf16_t* k2, long ldk2, const bf16_t* vt, long ldv, int ntiles) {
;     ...
;     for (int t = 0; t < ntiles; ++t) {
;         if (t + 2 < ntiles) gload(t + 2);
;         const LAS unsigned char* kb = lds + (t & 3) * BUF; const LAS unsigned char* vb = kb + KT;
;         f32x16 p[2];
;         {
;             bf16x8 kf[2][DQK / 16];
; #pragma unroll
;             for (int hf = 0; hf < 2; ++hf)
; #pragma unroll
;                 for (int d0 = 0; d0 < DQK / 16; ++d0) kf[hf][d0] = *(const LAS bf16x8*)(kb + (32 * hf + pr) * KROW + (16 * d0 + 8 * h) * 2);
;             __builtin_amdgcn_sched_barrier(0);
;             __builtin_amdgcn_s_setprio(2);
; #pragma unroll
;             for (int d0 = 0; d0 < DQK / 16; ++d0)
; #pragma unroll
;                 for (int hf = 0; hf < 2; ++hf) p[hf] = MFMA32(kf[hf][d0], qf[d0], d0 == 0 ? negm : p[hf]);
;             __builtin_amdgcn_sched_barrier(0);
;         }
;         constexpr int NBLK = DV / 32;
;         bf16x8 vk[2][NBLK];
;     ...
;         LDVK(0, 0);
;         __builtin_amdgcn_sched_barrier(0);
;         float ta = fmaxf(fmaxf(p[0][0], p[0][1]), p[1][0]), tb = fmaxf(fmaxf(p[0][2], p[0][3]), p[1][1]);
;         ta = fmaxf(fmaxf(ta, p[1][2]), p[1][3]);
; #pragma unroll
;         for (int i = 4; i < 16; i += 4) { ta = fmaxf(fmaxf(ta, p[0][i]), p[0][i + 1]); tb = fmaxf(fmaxf(tb, p[0][i + 2]), p[0][i + 3]); ta = fmaxf(fmaxf(ta, p[1][i]), p[1][i + 1]); tb = fmaxf(fmaxf(tb, p[1][i + 2]), p[1][i + 3]); }
;         float tm = fmaxf(ta, tb);
;         if (__any(t == 0 || tm > 8.0f)) {
;             tm = fmaxf(tm, __shfl_xor(tm, 32));
;             const float dl = (t == 0 || tm > 0.f) ? tm : 0.f; mrun += dl;
;             const float alpha = __builtin_amdgcn_exp2f(-dl); lrun *= alpha;
; #pragma unroll
;             for (int i = 0; i < 16; ++i) { p[0][i] -= dl; p[1][i] -= dl; negm[i] = -mrun; }
; #pragma unroll
;             for (int b = 0; b < DV / 32; ++b)
; #pragma unroll
;                 for (int i = 0; i < 16; ++i) o[b][i] *= alpha;
;         }
;         bf16x8 pf[4]; float rs = 0.f; u32x4 wq;
;     ...
;         EXPPART(0, 0); EXPPART(0, 1); EXPPART(0, 2); EXPPART(0, 3); pf[0] = __builtin_bit_cast(bf16x8, wq);
.Lml_nobar:
	v_add3_u32 v233, s8, v146, v141
	ds_read_b128 v[116:119], v233 offset:0
	ds_read_b128 v[120:123], v233 offset:32
	ds_read_b128 v[148:151], v233 offset:64
	ds_read_b128 v[152:155], v233 offset:96
	s_waitcnt lgkmcnt(2)
	v_mfma_f32_32x32x16_bf16 v[64:79], v[116:119], v[80:83], v[0:15]
	v_exp_f32_e32 v50, v50
	ds_read_b128 v[116:119], v233 offset:128
	v_add_f32_e32 v234, v222, v234
	v_exp_f32_e32 v58, v58
	v_add_f32_e32 v235, v223, v235
	v_mfma_f32_32x32x16_bf16 v[64:79], v[120:123], v[84:87], v[64:79]
	v_exp_f32_e32 v51, v51
	ds_read_b128 v[120:123], v233 offset:160
	v_add_f32_e32 v234, v224, v234
	v_exp_f32_e32 v59, v59
	v_add_f32_e32 v235, v225, v235
	v_cvt_pk_bf16_f32 v199, v50, v51
	s_waitcnt lgkmcnt(2)
	v_mfma_f32_32x32x16_bf16 v[64:79], v[148:151], v[88:91], v[64:79]
	v_exp_f32_e32 v52, v52
	ds_read_b128 v[148:151], v233 offset:6656
	v_add_f32_e32 v234, v226, v234
	v_exp_f32_e32 v60, v60
	v_add_f32_e32 v235, v227, v235
	v_mfma_f32_32x32x16_bf16 v[64:79], v[152:155], v[92:95], v[64:79]
	v_exp_f32_e32 v53, v53
	ds_read_b128 v[152:155], v233 offset:6688
	v_add_f32_e32 v234, v228, v234
	v_exp_f32_e32 v61, v61
	v_add_f32_e32 v235, v229, v235
	v_cvt_pk_bf16_f32 v200, v52, v53
	s_waitcnt lgkmcnt(2)
	v_mfma_f32_32x32x16_bf16 v[64:79], v[116:119], v[96:99], v[64:79]
	v_exp_f32_e32 v54, v54
	ds_read_b128 v[116:119], v233 offset:6720
	v_add_f32_e32 v234, v230, v234
	v_exp_f32_e32 v62, v62
	v_add_f32_e32 v235, v231, v235
	v_mfma_f32_32x32x16_bf16 v[64:79], v[120:123], v[100:103], v[64:79]
	v_exp_f32_e32 v55, v55
	ds_read_b128 v[120:123], v233 offset:6752
	s_nop 0
	v_exp_f32_e32 v63, v63
	v_cvt_pk_bf16_f32 v201, v54, v55
	v_mfma_f32_32x32x16_bf16 v[32:47], v[190:193], v[208:211], v[32:47]
	v_add_f32_e32 v234, v48, v234
	ds_read_b128 v[190:193], v232 offset:13408
	v_add_f32_e32 v235, v56, v235
	v_add_f32_e32 v234, v49, v234
	v_add_f32_e32 v235, v57, v235
	v_add_f32_e32 v234, v50, v234
	v_add_f32_e32 v234, v51, v234
	v_mfma_f32_32x32x16_bf16 v[16:31], v[194:197], v[208:211], v[16:31]
	v_add_f32_e32 v234, v52, v234
	ds_read_b128 v[194:197], v232 offset:18016
	v_add_f32_e32 v235, v58, v235
	v_add_f32_e32 v234, v53, v234
	v_add_f32_e32 v235, v59, v235
	v_add_f32_e32 v234, v54, v234
	v_add_f32_e32 v234, v55, v234
	v_add3_u32 v232, s8, v143, v141
	v_mfma_f32_32x32x16_bf16 v[32:47], v[158:161], v[198:201], v[32:47]
	v_cvt_pk_bf16_f32 v212, v56, v57
	ds_read_b128 v[158:161], v232 offset:13312
	v_add_f32_e32 v235, v60, v235
	v_cvt_pk_bf16_f32 v213, v58, v59
	v_add_f32_e32 v234, v61, v234
	v_exp_f32_e32 v216, v64
	v_mfma_f32_32x32x16_bf16 v[16:31], v[162:165], v[198:201], v[16:31]
	v_cvt_pk_bf16_f32 v214, v60, v61
	ds_read_b128 v[162:165], v232 offset:17920
	v_add_f32_e32 v235, v62, v235
	v_cvt_pk_bf16_f32 v215, v62, v63
	v_add_f32_e32 v234, v63, v234
	v_exp_f32_e32 v217, v65
	s_waitcnt lgkmcnt(6)
	v_mfma_f32_32x32x16_bf16 v[48:63], v[148:151], v[80:83], v[0:15]
	v_add_f32_e32 v234, v235, v234
	ds_read_b128 v[148:151], v233 offset:6784
	v_add_f32_e32 v147, v234, v147
	v_exp_f32_e32 v218, v66
	v_exp_f32_e32 v219, v67
	v_mfma_f32_32x32x16_bf16 v[48:63], v[152:155], v[84:87], v[48:63]
	v_exp_f32_e32 v220, v68
	ds_read_b128 v[152:155], v233 offset:6816
	v_exp_f32_e32 v221, v69
	v_cvt_pk_bf16_f32 v198, v216, v217
	s_waitcnt lgkmcnt(6)
	v_mfma_f32_32x32x16_bf16 v[48:63], v[116:119], v[88:91], v[48:63]
	v_exp_f32_e32 v222, v70
	v_exp_f32_e32 v223, v71
	v_cvt_pk_bf16_f32 v199, v218, v219
	s_waitcnt vmcnt(0)
	v_add3_u32 v233, s18, v144, v145
	ds_write_b128 v233, v[104:107] offset:0
	v_add_u32_e32 v233, s18, v236
	ds_write_b128 v233, v[108:111] offset:0
	v_add3_u32 v233, s18, v127, v126
	ds_write_b128 v233, v[112:115] offset:13312
	v_mfma_f32_32x32x16_bf16 v[48:63], v[120:123], v[92:95], v[48:63]
	v_exp_f32_e32 v224, v72
	v_exp_f32_e32 v225, v73
	v_cvt_pk_bf16_f32 v200, v220, v221
	s_waitcnt lgkmcnt(3)
	v_mfma_f32_32x32x16_bf16 v[48:63], v[148:151], v[96:99], v[48:63]
	v_exp_f32_e32 v226, v74
	v_exp_f32_e32 v227, v75
	v_cvt_pk_bf16_f32 v201, v222, v223
	v_mfma_f32_32x32x16_bf16 v[48:63], v[152:155], v[100:103], v[48:63]
	v_exp_f32_e32 v228, v76
	v_exp_f32_e32 v229, v77
	v_cvt_pk_bf16_f32 v208, v224, v225
	v_mfma_f32_32x32x16_bf16 v[32:47], v[190:193], v[212:215], v[32:47]
	v_exp_f32_e32 v230, v78
	ds_read_b128 v[190:193], v232 offset:13344
	v_exp_f32_e32 v231, v79
	v_cvt_pk_bf16_f32 v209, v226, v227
	v_mfma_f32_32x32x16_bf16 v[16:31], v[194:197], v[212:215], v[16:31]
	v_cvt_pk_bf16_f32 v210, v228, v229
	ds_read_b128 v[194:197], v232 offset:17952
	s_nop 0
	v_cvt_pk_bf16_f32 v211, v230, v231
	v_cmp_lt_f32_e32 vcc, 0x46800000, v234
	s_add_i32 s7, s7, 0x5800
	s_cmp_eq_u32 s7, 0x1b800
	s_cselect_b32 s7, 0, s7
	s_add_i32 s8, s8, 0x5800
	s_cmp_eq_u32 s8, 0x1b800
	s_cselect_b32 s8, 0, s8
	s_add_i32 s18, s18, 0x5800
	s_cmp_eq_u32 s18, 0x1b800
	s_cselect_b32 s18, 0, s18
	s_add_i32 s6, s6, 1
	s_cmp_eq_u32 s6, s5
	s_cbranch_scc1 .Lml_exit
	s_cbranch_vccnz .Lml_rare_l
	s_branch .Lml_top
